# baseline (speedup 1.0000x reference)
.LBB0_332:
	v_max_f32_e32 v3, v50, v51
	v_max3_f32 v3, v3, v52, v53
	v_max3_f32 v3, v3, v54, v55
	v_max3_f32 v3, v3, v56, v57
	v_max3_f32 v3, v3, v58, v59
	v_max3_f32 v3, v3, v60, v61
	v_max3_f32 v3, v3, v62, v63
	v_max3_f32 v3, v3, v64, v65
	v_max3_f32 v3, v3, v66, v67
	v_max3_f32 v3, v3, v68, v69
	v_max3_f32 v3, v3, v70, v71
	v_max3_f32 v3, v3, v72, v73
	v_max3_f32 v3, v3, v74, v75
	v_max3_f32 v3, v3, v76, v77
	v_max3_f32 v3, v3, v78, v79
	v_max3_f32 v3, v3, v80, v81
	v_mov_b32_e32 v4, v3
	s_nop 1
	v_permlane32_swap_b32_e32 v3, v4
	v_max_f32_e32 v3, v3, v4
	v_sub_f32_e32 v4, v3, v153
	v_mul_f32_e32 v4, 0x3db504f3, v4
	v_cmp_ge_f32_e32 vcc, s96, v4
	s_cmp_eq_u64 vcc, exec
	s_cselect_b64 s[8:9], -1, 0
	s_add_i32 s10, s74, 1
	s_cmp_ge_u32 s10, s33
	s_cselect_b64 s[10:11], -1, 0
	s_add_i32 s12, s73, 1
	v_max_f32_e32 v4, v153, v153
	s_cmp_gt_u32 s12, s1
	v_max_f32_e32 v155, v4, v3
	s_cselect_b64 s[12:13], -1, 0
	v_cndmask_b32_e64 v154, v155, v153, s[8:9]
	s_or_b64 s[12:13], s[10:11], s[12:13]
	s_mov_b64 s[10:11], -1
	s_and_b64 vcc, exec, s[12:13]
	v_mul_f32_e32 v3, 0xbe0293ee, v154
	s_cbranch_vccnz .LBB0_334
	s_and_b32 s10, s4, 0x4000
	s_nop 0
	v_or_b32_e32 v12, s10, v140
	v_add_u32_e32 v16, v12, v147
	v_add_u32_e32 v17, v12, v148
	v_add_u32_e32 v114, v12, v141
	v_add_u32_e32 v115, v12, v142
	v_add_u32_e32 v116, v12, v143
	v_add_u32_e32 v117, v12, v144
	v_add_u32_e32 v118, v12, v145
	ds_read_b128 v[4:7], v16
	v_add_u32_e32 v119, v12, v146
	ds_read_b128 v[8:11], v17
	v_fmamk_f32 v120, v54, 0x3e0293ee, v3
	v_fmamk_f32 v121, v55, 0x3e0293ee, v3
	v_fmamk_f32 v122, v57, 0x3e0293ee, v3
	v_fmamk_f32 v123, v58, 0x3e0293ee, v3
	v_fmamk_f32 v124, v59, 0x3e0293ee, v3
	v_fmamk_f32 v125, v60, 0x3e0293ee, v3
	v_fmamk_f32 v126, v61, 0x3e0293ee, v3
	ds_read_b128 v[12:15], v114
	s_waitcnt lgkmcnt(0)
	v_mfma_f32_32x32x16_bf16 v[34:49], v[12:15], v[82:85], 0
	v_fmamk_f32 v127, v62, 0x3e0293ee, v3
	v_fmamk_f32 v128, v63, 0x3e0293ee, v3
	v_fmamk_f32 v129, v64, 0x3e0293ee, v3
	v_fmamk_f32 v156, v65, 0x3e0293ee, v3
	v_fmamk_f32 v157, v66, 0x3e0293ee, v3
	v_fmamk_f32 v158, v67, 0x3e0293ee, v3
	v_fmamk_f32 v159, v68, 0x3e0293ee, v3
	v_fmamk_f32 v160, v69, 0x3e0293ee, v3
	ds_read_b128 v[12:15], v115
	s_waitcnt lgkmcnt(0)
	v_mfma_f32_32x32x16_bf16 v[34:49], v[12:15], v[86:89], v[34:49]
	v_fmamk_f32 v161, v70, 0x3e0293ee, v3
	v_fmamk_f32 v162, v71, 0x3e0293ee, v3
	ds_read_b128 v[12:15], v116
	v_exp_f32_e32 v120, v120
	v_exp_f32_e32 v121, v121
	v_exp_f32_e32 v122, v122
	v_exp_f32_e32 v123, v123
	s_waitcnt lgkmcnt(0)
	v_mfma_f32_32x32x16_bf16 v[34:49], v[12:15], v[90:93], v[34:49]
	ds_read_b128 v[12:15], v117
	v_exp_f32_e32 v124, v124
	v_exp_f32_e32 v125, v125
	v_exp_f32_e32 v126, v126
	v_exp_f32_e32 v127, v127
	v_exp_f32_e32 v128, v128
	v_exp_f32_e32 v129, v129
	s_waitcnt lgkmcnt(0)
	v_mfma_f32_32x32x16_bf16 v[34:49], v[12:15], v[94:97], v[34:49]
	ds_read_b128 v[12:15], v118
	v_exp_f32_e32 v172, v157
	v_exp_f32_e32 v158, v158
	v_exp_f32_e32 v159, v159
	v_exp_f32_e32 v160, v160
	v_exp_f32_e32 v161, v161
	v_exp_f32_e32 v162, v162
	s_waitcnt lgkmcnt(0)
	v_mfma_f32_32x32x16_bf16 v[34:49], v[12:15], v[98:101], v[34:49]
	ds_read_b128 v[12:15], v119
	s_mov_b64 s[10:11], 0
	s_waitcnt lgkmcnt(0)
	v_mfma_f32_32x32x16_bf16 v[34:49], v[12:15], v[102:105], v[34:49]
	v_fmamk_f32 v12, v50, 0x3e0293ee, v3
	v_fmamk_f32 v13, v51, 0x3e0293ee, v3
	v_fmamk_f32 v14, v52, 0x3e0293ee, v3
	v_fmamk_f32 v15, v53, 0x3e0293ee, v3
	v_exp_f32_e32 v12, v12
	v_exp_f32_e32 v13, v13
	v_exp_f32_e32 v14, v14
	v_mfma_f32_32x32x16_bf16 v[34:49], v[4:7], v[106:109], v[34:49]
	ds_read_b128 v[4:7], v17 offset:8192
	v_exp_f32_e32 v15, v15
	v_mfma_f32_32x32x16_bf16 v[34:49], v[8:11], v[110:113], v[34:49]
	v_fmamk_f32 v17, v56, 0x3e0293ee, v3
	ds_read_b128 v[8:11], v114 offset:8192
	v_exp_f32_e32 v17, v17
	s_waitcnt lgkmcnt(0)
	v_mfma_f32_32x32x16_bf16 v[18:33], v[8:11], v[82:85], 0
	ds_read_b128 v[8:11], v115 offset:8192
	s_waitcnt lgkmcnt(0)
	v_mfma_f32_32x32x16_bf16 v[18:33], v[8:11], v[86:89], v[18:33]
	v_add_f32_e32 v8, 0, v12
	v_add_f32_e32 v8, v13, v8
	v_add_f32_e32 v8, v14, v8
	v_add_f32_e32 v8, v15, v8
	v_add_f32_e32 v8, v120, v8
	v_add_f32_e32 v171, v121, v8
	ds_read_b128 v[8:11], v116 offset:8192
	s_waitcnt lgkmcnt(0)
	v_mfma_f32_32x32x16_bf16 v[18:33], v[8:11], v[90:93], v[18:33]
	v_add_f32_e32 v8, v17, v171
	v_add_f32_e32 v8, v122, v8
	v_add_f32_e32 v8, v123, v8
	v_add_f32_e32 v8, v124, v8
	v_add_f32_e32 v8, v125, v8
	v_add_f32_e32 v8, v126, v8
	v_add_f32_e32 v8, v127, v8
	v_add_f32_e32 v116, v128, v8
	ds_read_b128 v[8:11], v117 offset:8192
	v_exp_f32_e32 v171, v156
	s_waitcnt lgkmcnt(0)
	v_mfma_f32_32x32x16_bf16 v[18:33], v[8:11], v[94:97], v[18:33]
	v_add_f32_e32 v8, v129, v116
	v_add_f32_e32 v8, v171, v8
	v_add_f32_e32 v8, v172, v8
	v_add_f32_e32 v8, v158, v8
	v_add_f32_e32 v8, v159, v8
	v_add_f32_e32 v8, v160, v8
	v_add_f32_e32 v8, v161, v8
	v_add_f32_e32 v116, v162, v8
	ds_read_b128 v[8:11], v118 offset:8192
	s_waitcnt lgkmcnt(0)
	v_mfma_f32_32x32x16_bf16 v[18:33], v[8:11], v[98:101], v[18:33]
	v_fmamk_f32 v163, v73, 0x3e0293ee, v3
	v_fmamk_f32 v164, v74, 0x3e0293ee, v3
	v_fmamk_f32 v165, v75, 0x3e0293ee, v3
	v_fmamk_f32 v166, v76, 0x3e0293ee, v3
	v_fmamk_f32 v167, v77, 0x3e0293ee, v3
	v_fmamk_f32 v168, v78, 0x3e0293ee, v3
	v_fmamk_f32 v169, v79, 0x3e0293ee, v3
	v_fmamk_f32 v114, v72, 0x3e0293ee, v3
	v_exp_f32_e32 v173, v114
	v_exp_f32_e32 v163, v163
	v_exp_f32_e32 v164, v164
	v_exp_f32_e32 v165, v165
	v_exp_f32_e32 v166, v166
	v_add_f32_e32 v8, v173, v116
	v_exp_f32_e32 v167, v167
	v_add_f32_e32 v8, v163, v8
	v_exp_f32_e32 v168, v168
	v_add_f32_e32 v8, v164, v8
	v_exp_f32_e32 v169, v169
	v_add_f32_e32 v8, v165, v8
	v_add_f32_e32 v8, v166, v8
	v_add_f32_e32 v8, v167, v8
	v_add_f32_e32 v8, v168, v8
	v_add_f32_e32 v114, v169, v8
	ds_read_b128 v[8:11], v119 offset:8192
	s_waitcnt lgkmcnt(0)
	v_mfma_f32_32x32x16_bf16 v[18:33], v[8:11], v[102:105], v[18:33]
	v_fmamk_f32 v170, v81, 0x3e0293ee, v3
	v_fmamk_f32 v115, v80, 0x3e0293ee, v3
	v_exp_f32_e32 v174, v115
	v_exp_f32_e32 v170, v170
	v_add_f32_e32 v8, v174, v114
	v_add_f32_e32 v156, v170, v8
	ds_read_b128 v[8:11], v16 offset:8192
	s_waitcnt lgkmcnt(0)
	v_mfma_f32_32x32x16_bf16 v[18:33], v[8:11], v[106:109], v[18:33]
	v_cvt_pk_bf16_f32 v114, v12, v13
	v_cvt_pk_bf16_f32 v115, v14, v15
	v_cvt_pk_bf16_f32 v116, v120, v121
	v_cvt_pk_bf16_f32 v117, v17, v122
	v_cvt_pk_bf16_f32 v118, v123, v124
	v_cvt_pk_bf16_f32 v119, v125, v126
	v_cvt_pk_bf16_f32 v120, v127, v128
	v_mfma_f32_32x32x16_bf16 v[18:33], v[4:7], v[110:113], v[18:33]
	v_cvt_pk_bf16_f32 v121, v129, v171
	v_cvt_pk_bf16_f32 v122, v172, v158
	v_cvt_pk_bf16_f32 v123, v159, v160
	v_cvt_pk_bf16_f32 v124, v161, v162
	v_cvt_pk_bf16_f32 v125, v173, v163
	v_cvt_pk_bf16_f32 v126, v164, v165
	v_cvt_pk_bf16_f32 v127, v166, v167
	v_cvt_pk_bf16_f32 v128, v168, v169
	v_cvt_pk_bf16_f32 v129, v174, v170
	s_nop 0
	v_permlane32_swap_b32_e32 v119, v121
	v_permlane32_swap_b32_e32 v122, v124
	v_permlane32_swap_b32_e32 v123, v125
	v_permlane32_swap_b32_e32 v126, v128
	v_permlane32_swap_b32_e32 v127, v129
	v_mov_b32_e32 v157, v156
	s_nop 1
	v_permlane32_swap_b32_e32 v156, v157
	v_permlane32_swap_b32_e32 v114, v116
	v_permlane32_swap_b32_e32 v115, v117
	v_permlane32_swap_b32_e32 v118, v120

.LBB0_391:
	s_nop 9
	v_max_f32_e32 v3, v98, v99
	v_max3_f32 v3, v3, v100, v101
	v_max3_f32 v3, v3, v102, v103
	v_max3_f32 v3, v3, v104, v105
	v_max3_f32 v3, v3, v106, v107
	v_max3_f32 v3, v3, v108, v109
	v_max3_f32 v3, v3, v110, v111
	v_max3_f32 v3, v3, v112, v113
	v_max3_f32 v3, v3, v82, v83
	v_max3_f32 v3, v3, v84, v85
	v_max3_f32 v3, v3, v86, v87
	v_max3_f32 v3, v3, v88, v89
	v_max3_f32 v3, v3, v90, v91
	v_max3_f32 v3, v3, v92, v93
	v_max3_f32 v3, v3, v94, v95
	v_max3_f32 v3, v3, v96, v97
	v_mov_b32_e32 v4, v3
	s_nop 1
	v_permlane32_swap_b32_e32 v3, v4
	v_max_f32_e32 v3, v3, v4
	v_sub_f32_e32 v4, v3, v232
	v_mul_f32_e32 v4, 0x3d93cd3a, v4
	v_cmp_ge_f32_e32 vcc, s96, v4
	v_max_f32_e32 v5, v232, v232
	s_cmp_eq_u64 vcc, exec
	v_max_f32_e32 v5, v5, v3
	s_cselect_b64 vcc, -1, 0
	v_sub_f32_e32 v3, v232, v5
	v_cndmask_b32_e32 v232, v5, v232, vcc
	v_mul_f32_e32 v4, 0xbdd53b94, v232
	v_fmamk_f32 v5, v98, 0x3dd53b94, v4
	v_fmamk_f32 v6, v99, 0x3dd53b94, v4
	v_exp_f32_e32 v5, v5
	v_fmamk_f32 v7, v100, 0x3dd53b94, v4
	v_exp_f32_e32 v6, v6
	v_fmamk_f32 v8, v101, 0x3dd53b94, v4
	v_exp_f32_e32 v7, v7
	v_fmamk_f32 v9, v102, 0x3dd53b94, v4
	v_fmamk_f32 v10, v103, 0x3dd53b94, v4
	v_fmamk_f32 v11, v104, 0x3dd53b94, v4
	v_fmamk_f32 v12, v105, 0x3dd53b94, v4
	v_fmamk_f32 v13, v106, 0x3dd53b94, v4
	v_fmamk_f32 v14, v107, 0x3dd53b94, v4
	v_fmamk_f32 v15, v108, 0x3dd53b94, v4
	v_fmamk_f32 v16, v109, 0x3dd53b94, v4
	v_fmamk_f32 v17, v110, 0x3dd53b94, v4
	v_fmamk_f32 v98, v111, 0x3dd53b94, v4
	v_fmamk_f32 v99, v112, 0x3dd53b94, v4
	v_fmamk_f32 v100, v113, 0x3dd53b94, v4
	v_fmamk_f32 v82, v82, 0x3dd53b94, v4
	v_fmamk_f32 v83, v83, 0x3dd53b94, v4
	v_fmamk_f32 v84, v84, 0x3dd53b94, v4
	v_fmamk_f32 v85, v85, 0x3dd53b94, v4
	v_fmamk_f32 v86, v86, 0x3dd53b94, v4
	v_fmamk_f32 v87, v87, 0x3dd53b94, v4
	v_fmamk_f32 v88, v88, 0x3dd53b94, v4
	v_fmamk_f32 v89, v89, 0x3dd53b94, v4
	v_fmamk_f32 v90, v90, 0x3dd53b94, v4
	v_fmamk_f32 v91, v91, 0x3dd53b94, v4
	v_fmamk_f32 v92, v92, 0x3dd53b94, v4
	v_fmamk_f32 v93, v93, 0x3dd53b94, v4
	v_fmamk_f32 v94, v94, 0x3dd53b94, v4
	v_fmamk_f32 v95, v95, 0x3dd53b94, v4
	v_fmamk_f32 v96, v96, 0x3dd53b94, v4
	v_fmac_f32_e32 v4, 0x3dd53b94, v97
	v_exp_f32_e32 v8, v8
	v_exp_f32_e32 v9, v9
	v_exp_f32_e32 v102, v4
	v_add_f32_e32 v4, 0, v5
	v_exp_f32_e32 v10, v10
	v_add_f32_e32 v4, v6, v4
	v_exp_f32_e32 v11, v11
	v_add_f32_e32 v4, v7, v4
	v_exp_f32_e32 v12, v12
	v_add_f32_e32 v4, v8, v4
	v_exp_f32_e32 v13, v13
	v_add_f32_e32 v4, v9, v4
	v_exp_f32_e32 v14, v14
	v_add_f32_e32 v4, v10, v4
	v_exp_f32_e32 v15, v15
	v_add_f32_e32 v4, v11, v4
	v_exp_f32_e32 v97, v16
	v_add_f32_e32 v4, v12, v4
	v_exp_f32_e32 v101, v17
	v_add_f32_e32 v4, v13, v4
	v_exp_f32_e32 v98, v98
	v_add_f32_e32 v4, v14, v4
	v_exp_f32_e32 v99, v99
	v_add_f32_e32 v4, v15, v4
	v_exp_f32_e32 v100, v100
	v_add_f32_e32 v4, v97, v4
	v_exp_f32_e32 v82, v82
	v_add_f32_e32 v4, v101, v4
	v_exp_f32_e32 v83, v83
	v_add_f32_e32 v4, v98, v4
	v_exp_f32_e32 v84, v84
	v_add_f32_e32 v4, v99, v4
	v_exp_f32_e32 v85, v85
	v_add_f32_e32 v4, v100, v4
	v_exp_f32_e32 v86, v86
	v_add_f32_e32 v4, v82, v4
	v_exp_f32_e32 v87, v87
	v_add_f32_e32 v4, v83, v4
	v_exp_f32_e32 v88, v88
	v_add_f32_e32 v4, v84, v4
	v_exp_f32_e32 v89, v89
	v_add_f32_e32 v4, v85, v4
	v_exp_f32_e32 v90, v90
	v_add_f32_e32 v4, v86, v4
	v_exp_f32_e32 v91, v91
	v_add_f32_e32 v4, v87, v4
	v_exp_f32_e32 v92, v92
	v_add_f32_e32 v4, v88, v4
	v_exp_f32_e32 v93, v93
	v_add_f32_e32 v4, v89, v4
	v_exp_f32_e32 v94, v94
	v_add_f32_e32 v4, v90, v4
	v_exp_f32_e32 v95, v95
	v_add_f32_e32 v4, v91, v4
	v_exp_f32_e32 v96, v96
	v_add_f32_e32 v4, v92, v4
	v_mul_f32_e32 v3, 0x3dd53b94, v3
	v_add_f32_e32 v4, v93, v4
	v_exp_f32_e32 v3, v3
	v_add_f32_e32 v4, v94, v4
	v_add_f32_e32 v4, v95, v4
	v_add_f32_e32 v4, v96, v4
	v_add_f32_e32 v16, v102, v4
	v_cndmask_b32_e64 v3, v3, 1.0, vcc
	v_mov_b32_e32 v17, v16
	v_cvt_pk_bf16_f32 v4, v5, v6
	v_cvt_pk_bf16_f32 v5, v7, v8
	v_cvt_pk_bf16_f32 v6, v9, v10
	v_cvt_pk_bf16_f32 v7, v11, v12
	v_cvt_pk_bf16_f32 v8, v13, v14
	v_cvt_pk_bf16_f32 v9, v15, v97
	v_cvt_pk_bf16_f32 v10, v101, v98
	v_cvt_pk_bf16_f32 v11, v99, v100
	v_cvt_pk_bf16_f32 v12, v82, v83
	v_cvt_pk_bf16_f32 v13, v84, v85
	v_cvt_pk_bf16_f32 v14, v86, v87
	v_cvt_pk_bf16_f32 v15, v88, v89
	v_cvt_pk_bf16_f32 v82, v90, v91
	v_cvt_pk_bf16_f32 v83, v92, v93
	v_cvt_pk_bf16_f32 v84, v94, v95
	v_cvt_pk_bf16_f32 v85, v96, v102
	s_nop 1
	v_permlane32_swap_b32_e32 v16, v17
	v_permlane32_swap_b32_e32 v4, v6
	v_permlane32_swap_b32_e32 v5, v7
	v_permlane32_swap_b32_e32 v8, v10
	v_permlane32_swap_b32_e32 v9, v11
	v_permlane32_swap_b32_e32 v12, v14
	v_permlane32_swap_b32_e32 v13, v15
	v_permlane32_swap_b32_e32 v82, v84
	v_permlane32_swap_b32_e32 v83, v85
	v_cmp_gt_f32_e32 vcc, 1.0, v3
	s_cbranch_vccz .LBB0_395
	s_and_saveexec_b64 s[8:9], s[6:7]
	ds_write_b32 v226, v3 offset:128
	s_or_b64 exec, exec, s[8:9]
	s_waitcnt lgkmcnt(0)
	ds_read_b128 v[86:89], v214 offset:224
	ds_read_b128 v[90:93], v214 offset:192
	ds_read_b128 v[94:97], v214 offset:160
	ds_read_b128 v[98:101], v214 offset:128
	s_waitcnt lgkmcnt(3)
	v_pk_mul_f32 v[80:81], v[80:81], v[88:89]
	s_waitcnt lgkmcnt(2)
	v_pk_mul_f32 v[76:77], v[76:77], v[92:93]
	s_waitcnt lgkmcnt(1)
	v_pk_mul_f32 v[72:73], v[72:73], v[96:97]
	s_waitcnt lgkmcnt(0)
	v_pk_mul_f32 v[68:69], v[68:69], v[100:101]
	v_pk_mul_f32 v[78:79], v[78:79], v[86:87]
	v_pk_mul_f32 v[74:75], v[74:75], v[90:91]
	v_pk_mul_f32 v[70:71], v[70:71], v[94:95]
	v_pk_mul_f32 v[66:67], v[66:67], v[98:99]
	v_pk_mul_f32 v[64:65], v[64:65], v[88:89]
	v_pk_mul_f32 v[60:61], v[60:61], v[92:93]
	v_pk_mul_f32 v[56:57], v[56:57], v[96:97]
	v_pk_mul_f32 v[52:53], v[52:53], v[100:101]
	v_pk_mul_f32 v[62:63], v[62:63], v[86:87]
	v_pk_mul_f32 v[58:59], v[58:59], v[90:91]
	v_pk_mul_f32 v[54:55], v[54:55], v[94:95]
	v_pk_mul_f32 v[50:51], v[50:51], v[98:99]
	v_pk_mul_f32 v[48:49], v[48:49], v[88:89]
	v_pk_mul_f32 v[44:45], v[44:45], v[92:93]
	v_pk_mul_f32 v[40:41], v[40:41], v[96:97]
	v_pk_mul_f32 v[36:37], v[36:37], v[100:101]
	v_pk_mul_f32 v[46:47], v[46:47], v[86:87]
	v_pk_mul_f32 v[42:43], v[42:43], v[90:91]
	v_pk_mul_f32 v[38:39], v[38:39], v[94:95]
	v_pk_mul_f32 v[34:35], v[34:35], v[98:99]
	v_pk_mul_f32 v[32:33], v[32:33], v[88:89]
	v_pk_mul_f32 v[28:29], v[28:29], v[92:93]
	v_pk_mul_f32 v[24:25], v[24:25], v[96:97]
	v_pk_mul_f32 v[20:21], v[20:21], v[100:101]
	v_pk_mul_f32 v[30:31], v[30:31], v[86:87]
	v_pk_mul_f32 v[26:27], v[26:27], v[90:91]
	v_pk_mul_f32 v[22:23], v[22:23], v[94:95]
	v_pk_mul_f32 v[18:19], v[18:19], v[98:99]
